# FFN-up SwiGLU epilogues (both FFNs) rewritten by hand: same f32 function with fewer VALU ops per output (dequant scales folded into one exp argument multiply and one fma before the rcp), batched by 8
# speedup vs baseline: 1.0104x; 1.0057x over previous
; __device__ __forceinline__ float silu_f(float x) { return x * __builtin_amdgcn_rcpf(1.0f + __builtin_amdgcn_exp2f(-1.4426950408889634f * x)); }
; __device__ __forceinline__ float silu_f(float x) { return x * __builtin_amdgcn_rcpf(1.0f + __builtin_amdgcn_exp2f(-1.4426950408889634f * x)); }
; __device__ __forceinline__ float clamp8(float x) { return __builtin_amdgcn_fmed3f(x, -448.0f, 448.0f); }
; __device__ __forceinline__ unsigned pk4_fp8(float a, float b, float c, float d) {
;     int w = __builtin_amdgcn_cvt_pk_fp8_f32(clamp8(a), clamp8(b), 0, false); w = __builtin_amdgcn_cvt_pk_fp8_f32(clamp8(c), clamp8(d), w, true); return (unsigned)w; }
;     __device__ __forceinline__ void operator()(const f32x4 (&acc)[2][2][4][2], const Unit& u, int wr, int wc, int fr, int fq) const {
;         const int row0 = u.pm * BM + wr * 64 + fr, col0 = u.pn * HALF + wc * 32 + 8 * fq;
; #pragma unroll
;         for (int ai = 0; ai < 2; ++ai)
; #pragma unroll
;             for (int m = 0; m < 4; ++m) { unsigned char* rowp = O + (size_t)(row0 + ai * HALF + m * 16) * ldc + col0;
;                 const f32x4 g0 = acc[ai][0][m][0] * inv, g1 = acc[ai][0][m][1] * inv, u0 = acc[ai][1][m][0] * (inv * oscale), u1 = acc[ai][1][m][1] * (inv * oscale);
;                 unsigned w0 = pk4_fp8(silu_f(g0[0]) * u0[0], silu_f(g0[1]) * u0[1], silu_f(g0[2]) * u0[2], silu_f(g0[3]) * u0[3]);
;                 unsigned w1 = pk4_fp8(silu_f(g1[0]) * u1[0], silu_f(g1[1]) * u1[1], silu_f(g1[2]) * u1[2], silu_f(g1[3]) * u1[3]);
;                 typedef unsigned u32x2_t __attribute__((ext_vector_type(2))); *(u32x2_t*)rowp = (u32x2_t){w0, w1}; }
.LBB0_193:
	v_mov_b32_e32 v132, v252
	s_lshl_b32 s15, s22, 8
	s_add_i32 s15, s15, s45
	v_and_or_b32 v146, v132, 15, s15
	s_lshl_b32 s15, s53, 7
	v_lshrrev_b32_e32 v132, 1, v132
	v_and_or_b32 v132, v132, 24, s15
	v_or_b32_e32 v136, s46, v132
	v_ashrrev_i32_e32 v137, 31, v136
	v_mov_b64_e32 v[138:139], s[6:7]
	v_mov_b32_e32 v133, s12
	v_mov_b32_e32 v135, s10
	v_mul_f32_e32 v133, s10, v133
	v_mul_f32_e32 v134, 0xbfb8aa3b, v135
	v_rcp_f32_e32 v133, v133
	s_nop 1
	v_readfirstlane_b32 s28, v134
	v_readfirstlane_b32 s29, v133
	s_nop 1
	v_mul_f32_e32 v116, v124, v116
	v_mul_f32_e32 v117, v125, v117
	v_mul_f32_e32 v118, v126, v118
	v_mul_f32_e32 v119, v127, v119
	v_mul_f32_e32 v112, v120, v112
	v_mul_f32_e32 v113, v121, v113
	v_mul_f32_e32 v114, v122, v114
	v_mul_f32_e32 v115, v123, v115
	v_mul_f32_e32 v124, s28, v124
	v_mul_f32_e32 v125, s28, v125
	v_mul_f32_e32 v126, s28, v126
	v_mul_f32_e32 v127, s28, v127
	v_mul_f32_e32 v120, s28, v120
	v_mul_f32_e32 v121, s28, v121
	v_mul_f32_e32 v122, s28, v122
	v_mul_f32_e32 v123, s28, v123
	v_exp_f32_e32 v124, v124
	v_exp_f32_e32 v125, v125
	v_exp_f32_e32 v126, v126
	v_exp_f32_e32 v127, v127
	v_exp_f32_e32 v120, v120
	v_exp_f32_e32 v121, v121
	v_exp_f32_e32 v122, v122
	v_exp_f32_e32 v123, v123
	v_fma_f32 v124, v124, s29, s29
	v_fma_f32 v125, v125, s29, s29
	v_fma_f32 v126, v126, s29, s29
	v_fma_f32 v127, v127, s29, s29
	v_fma_f32 v120, v120, s29, s29
	v_fma_f32 v121, v121, s29, s29
	v_fma_f32 v122, v122, s29, s29
	v_fma_f32 v123, v123, s29, s29
	v_rcp_f32_e32 v124, v124
	v_rcp_f32_e32 v125, v125
	v_rcp_f32_e32 v126, v126
	v_rcp_f32_e32 v127, v127
	v_rcp_f32_e32 v120, v120
	v_rcp_f32_e32 v121, v121
	v_rcp_f32_e32 v122, v122
	v_rcp_f32_e32 v123, v123
	v_mul_f32_e32 v116, v116, v124
	v_mul_f32_e32 v117, v117, v125
	v_mul_f32_e32 v118, v118, v126
	v_mul_f32_e32 v119, v119, v127
	v_mul_f32_e32 v112, v112, v120
	v_mul_f32_e32 v113, v113, v121
	v_mul_f32_e32 v114, v114, v122
	v_mul_f32_e32 v115, v115, v123
	v_med3_f32 v116, v116, s52, v145
	v_med3_f32 v117, v117, s52, v145
	v_med3_f32 v118, v118, s52, v145
	v_med3_f32 v119, v119, s52, v145
	v_med3_f32 v112, v112, s52, v145
	v_med3_f32 v113, v113, s52, v145
	v_med3_f32 v114, v114, s52, v145
	v_med3_f32 v115, v115, s52, v145
	v_cvt_pk_fp8_f32 v132, v116, v117
	v_cvt_pk_fp8_f32 v132, v118, v119 op_sel:[0,0,1]
	v_cvt_pk_fp8_f32 v133, v112, v113
	v_cvt_pk_fp8_f32 v133, v114, v115 op_sel:[0,0,1]
	v_mad_i64_i32 v[126:127], s[24:25], v146, s51, v[138:139]
	v_lshl_add_u64 v[126:127], v[126:127], 0, v[136:137]
	global_store_dwordx2 v[126:127], v[132:133], off
	v_mul_f32_e32 v100, v108, v100
	v_mul_f32_e32 v101, v109, v101
	v_mul_f32_e32 v102, v110, v102
	v_mul_f32_e32 v103, v111, v103
	v_mul_f32_e32 v96, v104, v96
	v_mul_f32_e32 v97, v105, v97
	v_mul_f32_e32 v98, v106, v98
	v_mul_f32_e32 v99, v107, v99
	v_mul_f32_e32 v108, s28, v108
	v_mul_f32_e32 v109, s28, v109
	v_mul_f32_e32 v110, s28, v110
	v_mul_f32_e32 v111, s28, v111
	v_mul_f32_e32 v104, s28, v104
	v_mul_f32_e32 v105, s28, v105
	v_mul_f32_e32 v106, s28, v106
	v_mul_f32_e32 v107, s28, v107
	v_exp_f32_e32 v108, v108
	v_exp_f32_e32 v109, v109
	v_exp_f32_e32 v110, v110
	v_exp_f32_e32 v111, v111
	v_exp_f32_e32 v104, v104
	v_exp_f32_e32 v105, v105
	v_exp_f32_e32 v106, v106
	v_exp_f32_e32 v107, v107
	v_fma_f32 v108, v108, s29, s29
	v_fma_f32 v109, v109, s29, s29
	v_fma_f32 v110, v110, s29, s29
	v_fma_f32 v111, v111, s29, s29
	v_fma_f32 v104, v104, s29, s29
	v_fma_f32 v105, v105, s29, s29
	v_fma_f32 v106, v106, s29, s29
	v_fma_f32 v107, v107, s29, s29
	v_rcp_f32_e32 v108, v108
	v_rcp_f32_e32 v109, v109
	v_rcp_f32_e32 v110, v110
	v_rcp_f32_e32 v111, v111
	v_rcp_f32_e32 v104, v104
	v_rcp_f32_e32 v105, v105
	v_rcp_f32_e32 v106, v106
	v_rcp_f32_e32 v107, v107
	v_mul_f32_e32 v100, v100, v108
	v_mul_f32_e32 v101, v101, v109
	v_mul_f32_e32 v102, v102, v110
	v_mul_f32_e32 v103, v103, v111
	v_mul_f32_e32 v96, v96, v104
	v_mul_f32_e32 v97, v97, v105
	v_mul_f32_e32 v98, v98, v106
	v_mul_f32_e32 v99, v99, v107
	v_med3_f32 v100, v100, s52, v145
	v_med3_f32 v101, v101, s52, v145
	v_med3_f32 v102, v102, s52, v145
	v_med3_f32 v103, v103, s52, v145
	v_med3_f32 v96, v96, s52, v145
	v_med3_f32 v97, v97, s52, v145
	v_med3_f32 v98, v98, s52, v145
	v_med3_f32 v99, v99, s52, v145
	v_cvt_pk_fp8_f32 v134, v100, v101
	v_cvt_pk_fp8_f32 v134, v102, v103 op_sel:[0,0,1]
	v_cvt_pk_fp8_f32 v135, v96, v97
	v_cvt_pk_fp8_f32 v135, v98, v99 op_sel:[0,0,1]
	v_add_u32_e32 v108, 0x10, v146
	v_mad_i64_i32 v[110:111], s[24:25], v108, s51, v[138:139]
	v_lshl_add_u64 v[110:111], v[110:111], 0, v[136:137]
	global_store_dwordx2 v[110:111], v[134:135], off
	v_mul_f32_e32 v84, v92, v84
	v_mul_f32_e32 v85, v93, v85
	v_mul_f32_e32 v86, v94, v86
	v_mul_f32_e32 v87, v95, v87
	v_mul_f32_e32 v80, v88, v80
	v_mul_f32_e32 v81, v89, v81
	v_mul_f32_e32 v82, v90, v82
	v_mul_f32_e32 v83, v91, v83
	v_mul_f32_e32 v92, s28, v92
	v_mul_f32_e32 v93, s28, v93
	v_mul_f32_e32 v94, s28, v94
	v_mul_f32_e32 v95, s28, v95
	v_mul_f32_e32 v88, s28, v88
	v_mul_f32_e32 v89, s28, v89
	v_mul_f32_e32 v90, s28, v90
	v_mul_f32_e32 v91, s28, v91
	v_exp_f32_e32 v92, v92
	v_exp_f32_e32 v93, v93
	v_exp_f32_e32 v94, v94
	v_exp_f32_e32 v95, v95
	v_exp_f32_e32 v88, v88
	v_exp_f32_e32 v89, v89
	v_exp_f32_e32 v90, v90
	v_exp_f32_e32 v91, v91
	v_fma_f32 v92, v92, s29, s29
	v_fma_f32 v93, v93, s29, s29
	v_fma_f32 v94, v94, s29, s29
	v_fma_f32 v95, v95, s29, s29
	v_fma_f32 v88, v88, s29, s29
	v_fma_f32 v89, v89, s29, s29
	v_fma_f32 v90, v90, s29, s29
	v_fma_f32 v91, v91, s29, s29
	v_rcp_f32_e32 v92, v92
	v_rcp_f32_e32 v93, v93
	v_rcp_f32_e32 v94, v94
	v_rcp_f32_e32 v95, v95
	v_rcp_f32_e32 v88, v88
; __device__ __forceinline__ float silu_f(float x) { return x * __builtin_amdgcn_rcpf(1.0f + __builtin_amdgcn_exp2f(-1.4426950408889634f * x)); }
; __device__ __forceinline__ float silu_f(float x) { return x * __builtin_amdgcn_rcpf(1.0f + __builtin_amdgcn_exp2f(-1.4426950408889634f * x)); }
; __device__ __forceinline__ float clamp8(float x) { return __builtin_amdgcn_fmed3f(x, -448.0f, 448.0f); }
; __device__ __forceinline__ unsigned pk4_fp8(float a, float b, float c, float d) {
;     int w = __builtin_amdgcn_cvt_pk_fp8_f32(clamp8(a), clamp8(b), 0, false); w = __builtin_amdgcn_cvt_pk_fp8_f32(clamp8(c), clamp8(d), w, true); return (unsigned)w; }
;     __device__ __forceinline__ void operator()(const f32x4 (&acc)[2][2][4][2], const Unit& u, int wr, int wc, int fr, int fq) const {
;         const int row0 = u.pm * BM + wr * 64 + fr, col0 = u.pn * HALF + wc * 32 + 8 * fq;
; #pragma unroll
;         for (int ai = 0; ai < 2; ++ai)
; #pragma unroll
;             for (int m = 0; m < 4; ++m) { unsigned char* rowp = O + (size_t)(row0 + ai * HALF + m * 16) * ldc + col0;
;                 const f32x4 g0 = acc[ai][0][m][0] * inv, g1 = acc[ai][0][m][1] * inv, u0 = acc[ai][1][m][0] * (inv * oscale), u1 = acc[ai][1][m][1] * (inv * oscale);
;                 unsigned w0 = pk4_fp8(silu_f(g0[0]) * u0[0], silu_f(g0[1]) * u0[1], silu_f(g0[2]) * u0[2], silu_f(g0[3]) * u0[3]);
;                 unsigned w1 = pk4_fp8(silu_f(g1[0]) * u1[0], silu_f(g1[1]) * u1[1], silu_f(g1[2]) * u1[2], silu_f(g1[3]) * u1[3]);
;                 typedef unsigned u32x2_t __attribute__((ext_vector_type(2))); *(u32x2_t*)rowp = (u32x2_t){w0, w1}; }
	v_rcp_f32_e32 v89, v89
	v_rcp_f32_e32 v90, v90
	v_rcp_f32_e32 v91, v91
	v_mul_f32_e32 v84, v84, v92
	v_mul_f32_e32 v85, v85, v93
	v_mul_f32_e32 v86, v86, v94
	v_mul_f32_e32 v87, v87, v95
	v_mul_f32_e32 v80, v80, v88
	v_mul_f32_e32 v81, v81, v89
	v_mul_f32_e32 v82, v82, v90
	v_mul_f32_e32 v83, v83, v91
	v_med3_f32 v84, v84, s52, v145
	v_med3_f32 v85, v85, s52, v145
	v_med3_f32 v86, v86, s52, v145
	v_med3_f32 v87, v87, s52, v145
	v_med3_f32 v80, v80, s52, v145
	v_med3_f32 v81, v81, s52, v145
	v_med3_f32 v82, v82, s52, v145
	v_med3_f32 v83, v83, s52, v145
	v_cvt_pk_fp8_f32 v132, v84, v85
	v_cvt_pk_fp8_f32 v132, v86, v87 op_sel:[0,0,1]
	v_cvt_pk_fp8_f32 v133, v80, v81
	v_cvt_pk_fp8_f32 v133, v82, v83 op_sel:[0,0,1]
	v_add_u32_e32 v92, 0x20, v146
	v_mad_i64_i32 v[94:95], s[24:25], v92, s51, v[138:139]
	v_lshl_add_u64 v[94:95], v[94:95], 0, v[136:137]
	global_store_dwordx2 v[94:95], v[132:133], off
	v_mul_f32_e32 v68, v76, v68
	v_mul_f32_e32 v69, v77, v69
	v_mul_f32_e32 v70, v78, v70
	v_mul_f32_e32 v71, v79, v71
	v_mul_f32_e32 v64, v72, v64
	v_mul_f32_e32 v65, v73, v65
	v_mul_f32_e32 v66, v74, v66
	v_mul_f32_e32 v67, v75, v67
	v_mul_f32_e32 v76, s28, v76
	v_mul_f32_e32 v77, s28, v77
	v_mul_f32_e32 v78, s28, v78
	v_mul_f32_e32 v79, s28, v79
	v_mul_f32_e32 v72, s28, v72
	v_mul_f32_e32 v73, s28, v73
	v_mul_f32_e32 v74, s28, v74
	v_mul_f32_e32 v75, s28, v75
	v_exp_f32_e32 v76, v76
	v_exp_f32_e32 v77, v77
	v_exp_f32_e32 v78, v78
	v_exp_f32_e32 v79, v79
	v_exp_f32_e32 v72, v72
	v_exp_f32_e32 v73, v73
	v_exp_f32_e32 v74, v74
	v_exp_f32_e32 v75, v75
	v_fma_f32 v76, v76, s29, s29
	v_fma_f32 v77, v77, s29, s29
	v_fma_f32 v78, v78, s29, s29
	v_fma_f32 v79, v79, s29, s29
	v_fma_f32 v72, v72, s29, s29
	v_fma_f32 v73, v73, s29, s29
	v_fma_f32 v74, v74, s29, s29
	v_fma_f32 v75, v75, s29, s29
	v_rcp_f32_e32 v76, v76
	v_rcp_f32_e32 v77, v77
	v_rcp_f32_e32 v78, v78
	v_rcp_f32_e32 v79, v79
	v_rcp_f32_e32 v72, v72
	v_rcp_f32_e32 v73, v73
	v_rcp_f32_e32 v74, v74
	v_rcp_f32_e32 v75, v75
	v_mul_f32_e32 v68, v68, v76
	v_mul_f32_e32 v69, v69, v77
	v_mul_f32_e32 v70, v70, v78
	v_mul_f32_e32 v71, v71, v79
	v_mul_f32_e32 v64, v64, v72
	v_mul_f32_e32 v65, v65, v73
	v_mul_f32_e32 v66, v66, v74
	v_mul_f32_e32 v67, v67, v75
	v_med3_f32 v68, v68, s52, v145
	v_med3_f32 v69, v69, s52, v145
	v_med3_f32 v70, v70, s52, v145
	v_med3_f32 v71, v71, s52, v145
	v_med3_f32 v64, v64, s52, v145
	v_med3_f32 v65, v65, s52, v145
	v_med3_f32 v66, v66, s52, v145
	v_med3_f32 v67, v67, s52, v145
	v_cvt_pk_fp8_f32 v134, v68, v69
	v_cvt_pk_fp8_f32 v134, v70, v71 op_sel:[0,0,1]
	v_cvt_pk_fp8_f32 v135, v64, v65
	v_cvt_pk_fp8_f32 v135, v66, v67 op_sel:[0,0,1]
	v_add_u32_e32 v76, 0x30, v146
	v_mad_i64_i32 v[78:79], s[24:25], v76, s51, v[138:139]
	v_lshl_add_u64 v[78:79], v[78:79], 0, v[136:137]
	global_store_dwordx2 v[78:79], v[134:135], off
	v_mul_f32_e32 v52, v60, v52
	v_mul_f32_e32 v53, v61, v53
	v_mul_f32_e32 v54, v62, v54
	v_mul_f32_e32 v55, v63, v55
	v_mul_f32_e32 v48, v56, v48
	v_mul_f32_e32 v49, v57, v49
	v_mul_f32_e32 v50, v58, v50
	v_mul_f32_e32 v51, v59, v51
	v_mul_f32_e32 v60, s28, v60
	v_mul_f32_e32 v61, s28, v61
	v_mul_f32_e32 v62, s28, v62
	v_mul_f32_e32 v63, s28, v63
	v_mul_f32_e32 v56, s28, v56
	v_mul_f32_e32 v57, s28, v57
	v_mul_f32_e32 v58, s28, v58
	v_mul_f32_e32 v59, s28, v59
	v_exp_f32_e32 v60, v60
	v_exp_f32_e32 v61, v61
	v_exp_f32_e32 v62, v62
	v_exp_f32_e32 v63, v63
	v_exp_f32_e32 v56, v56
	v_exp_f32_e32 v57, v57
	v_exp_f32_e32 v58, v58
	v_exp_f32_e32 v59, v59
	v_fma_f32 v60, v60, s29, s29
	v_fma_f32 v61, v61, s29, s29
	v_fma_f32 v62, v62, s29, s29
	v_fma_f32 v63, v63, s29, s29
	v_fma_f32 v56, v56, s29, s29
	v_fma_f32 v57, v57, s29, s29
	v_fma_f32 v58, v58, s29, s29
	v_fma_f32 v59, v59, s29, s29
	v_rcp_f32_e32 v60, v60
	v_rcp_f32_e32 v61, v61
	v_rcp_f32_e32 v62, v62
	v_rcp_f32_e32 v63, v63
	v_rcp_f32_e32 v56, v56
	v_rcp_f32_e32 v57, v57
	v_rcp_f32_e32 v58, v58
	v_rcp_f32_e32 v59, v59
	v_mul_f32_e32 v52, v52, v60
	v_mul_f32_e32 v53, v53, v61
	v_mul_f32_e32 v54, v54, v62
	v_mul_f32_e32 v55, v55, v63
	v_mul_f32_e32 v48, v48, v56
	v_mul_f32_e32 v49, v49, v57
	v_mul_f32_e32 v50, v50, v58
	v_mul_f32_e32 v51, v51, v59
	v_med3_f32 v52, v52, s52, v145
	v_med3_f32 v53, v53, s52, v145
	v_med3_f32 v54, v54, s52, v145
	v_med3_f32 v55, v55, s52, v145
	v_med3_f32 v48, v48, s52, v145
	v_med3_f32 v49, v49, s52, v145
	v_med3_f32 v50, v50, s52, v145
	v_med3_f32 v51, v51, s52, v145
	v_cvt_pk_fp8_f32 v132, v52, v53
	v_cvt_pk_fp8_f32 v132, v54, v55 op_sel:[0,0,1]
	v_cvt_pk_fp8_f32 v133, v48, v49
	v_cvt_pk_fp8_f32 v133, v50, v51 op_sel:[0,0,1]
	v_add_u32_e32 v60, 0x80, v146
	v_mad_i64_i32 v[62:63], s[24:25], v60, s51, v[138:139]
	v_lshl_add_u64 v[62:63], v[62:63], 0, v[136:137]
	global_store_dwordx2 v[62:63], v[132:133], off
	v_mul_f32_e32 v36, v44, v36
	v_mul_f32_e32 v37, v45, v37
	v_mul_f32_e32 v38, v46, v38
	v_mul_f32_e32 v39, v47, v39
	v_mul_f32_e32 v32, v40, v32
	v_mul_f32_e32 v33, v41, v33
	v_mul_f32_e32 v34, v42, v34
	v_mul_f32_e32 v35, v43, v35
	v_mul_f32_e32 v44, s28, v44
	v_mul_f32_e32 v45, s28, v45
	v_mul_f32_e32 v46, s28, v46
	v_mul_f32_e32 v47, s28, v47
	v_mul_f32_e32 v40, s28, v40
	v_mul_f32_e32 v41, s28, v41
	v_mul_f32_e32 v42, s28, v42
	v_mul_f32_e32 v43, s28, v43
	v_exp_f32_e32 v44, v44
	v_exp_f32_e32 v45, v45
	v_exp_f32_e32 v46, v46
	v_exp_f32_e32 v47, v47
	v_exp_f32_e32 v40, v40
; __device__ __forceinline__ float silu_f(float x) { return x * __builtin_amdgcn_rcpf(1.0f + __builtin_amdgcn_exp2f(-1.4426950408889634f * x)); }
; __device__ __forceinline__ float silu_f(float x) { return x * __builtin_amdgcn_rcpf(1.0f + __builtin_amdgcn_exp2f(-1.4426950408889634f * x)); }
; __device__ __forceinline__ float clamp8(float x) { return __builtin_amdgcn_fmed3f(x, -448.0f, 448.0f); }
; __device__ __forceinline__ unsigned pk4_fp8(float a, float b, float c, float d) {
;     int w = __builtin_amdgcn_cvt_pk_fp8_f32(clamp8(a), clamp8(b), 0, false); w = __builtin_amdgcn_cvt_pk_fp8_f32(clamp8(c), clamp8(d), w, true); return (unsigned)w; }
;     __device__ __forceinline__ void operator()(const f32x4 (&acc)[2][2][4][2], const Unit& u, int wr, int wc, int fr, int fq) const {
;         const int row0 = u.pm * BM + wr * 64 + fr, col0 = u.pn * HALF + wc * 32 + 8 * fq;
; #pragma unroll
;         for (int ai = 0; ai < 2; ++ai)
; #pragma unroll
;             for (int m = 0; m < 4; ++m) { unsigned char* rowp = O + (size_t)(row0 + ai * HALF + m * 16) * ldc + col0;
;                 const f32x4 g0 = acc[ai][0][m][0] * inv, g1 = acc[ai][0][m][1] * inv, u0 = acc[ai][1][m][0] * (inv * oscale), u1 = acc[ai][1][m][1] * (inv * oscale);
;                 unsigned w0 = pk4_fp8(silu_f(g0[0]) * u0[0], silu_f(g0[1]) * u0[1], silu_f(g0[2]) * u0[2], silu_f(g0[3]) * u0[3]);
;                 unsigned w1 = pk4_fp8(silu_f(g1[0]) * u1[0], silu_f(g1[1]) * u1[1], silu_f(g1[2]) * u1[2], silu_f(g1[3]) * u1[3]);
;                 typedef unsigned u32x2_t __attribute__((ext_vector_type(2))); *(u32x2_t*)rowp = (u32x2_t){w0, w1}; }
	v_exp_f32_e32 v41, v41
	v_exp_f32_e32 v42, v42
	v_exp_f32_e32 v43, v43
	v_fma_f32 v44, v44, s29, s29
	v_fma_f32 v45, v45, s29, s29
	v_fma_f32 v46, v46, s29, s29
	v_fma_f32 v47, v47, s29, s29
	v_fma_f32 v40, v40, s29, s29
	v_fma_f32 v41, v41, s29, s29
	v_fma_f32 v42, v42, s29, s29
	v_fma_f32 v43, v43, s29, s29
	v_rcp_f32_e32 v44, v44
	v_rcp_f32_e32 v45, v45
	v_rcp_f32_e32 v46, v46
	v_rcp_f32_e32 v47, v47
	v_rcp_f32_e32 v40, v40
	v_rcp_f32_e32 v41, v41
	v_rcp_f32_e32 v42, v42
	v_rcp_f32_e32 v43, v43
	v_mul_f32_e32 v36, v36, v44
	v_mul_f32_e32 v37, v37, v45
	v_mul_f32_e32 v38, v38, v46
	v_mul_f32_e32 v39, v39, v47
	v_mul_f32_e32 v32, v32, v40
	v_mul_f32_e32 v33, v33, v41
	v_mul_f32_e32 v34, v34, v42
	v_mul_f32_e32 v35, v35, v43
	v_med3_f32 v36, v36, s52, v145
	v_med3_f32 v37, v37, s52, v145
	v_med3_f32 v38, v38, s52, v145
	v_med3_f32 v39, v39, s52, v145
	v_med3_f32 v32, v32, s52, v145
	v_med3_f32 v33, v33, s52, v145
	v_med3_f32 v34, v34, s52, v145
	v_med3_f32 v35, v35, s52, v145
	v_cvt_pk_fp8_f32 v134, v36, v37
	v_cvt_pk_fp8_f32 v134, v38, v39 op_sel:[0,0,1]
	v_cvt_pk_fp8_f32 v135, v32, v33
	v_cvt_pk_fp8_f32 v135, v34, v35 op_sel:[0,0,1]
	v_add_u32_e32 v44, 0x90, v146
	v_mad_i64_i32 v[46:47], s[24:25], v44, s51, v[138:139]
	v_lshl_add_u64 v[46:47], v[46:47], 0, v[136:137]
	global_store_dwordx2 v[46:47], v[134:135], off
	v_mul_f32_e32 v20, v28, v20
	v_mul_f32_e32 v21, v29, v21
	v_mul_f32_e32 v22, v30, v22
	v_mul_f32_e32 v23, v31, v23
	v_mul_f32_e32 v16, v24, v16
	v_mul_f32_e32 v17, v25, v17
	v_mul_f32_e32 v18, v26, v18
	v_mul_f32_e32 v19, v27, v19
	v_mul_f32_e32 v28, s28, v28
	v_mul_f32_e32 v29, s28, v29
	v_mul_f32_e32 v30, s28, v30
	v_mul_f32_e32 v31, s28, v31
	v_mul_f32_e32 v24, s28, v24
	v_mul_f32_e32 v25, s28, v25
	v_mul_f32_e32 v26, s28, v26
	v_mul_f32_e32 v27, s28, v27
	v_exp_f32_e32 v28, v28
	v_exp_f32_e32 v29, v29
	v_exp_f32_e32 v30, v30
	v_exp_f32_e32 v31, v31
	v_exp_f32_e32 v24, v24
	v_exp_f32_e32 v25, v25
	v_exp_f32_e32 v26, v26
	v_exp_f32_e32 v27, v27
	v_fma_f32 v28, v28, s29, s29
	v_fma_f32 v29, v29, s29, s29
	v_fma_f32 v30, v30, s29, s29
	v_fma_f32 v31, v31, s29, s29
	v_fma_f32 v24, v24, s29, s29
	v_fma_f32 v25, v25, s29, s29
	v_fma_f32 v26, v26, s29, s29
	v_fma_f32 v27, v27, s29, s29
	v_rcp_f32_e32 v28, v28
	v_rcp_f32_e32 v29, v29
	v_rcp_f32_e32 v30, v30
	v_rcp_f32_e32 v31, v31
	v_rcp_f32_e32 v24, v24
	v_rcp_f32_e32 v25, v25
	v_rcp_f32_e32 v26, v26
	v_rcp_f32_e32 v27, v27
	v_mul_f32_e32 v20, v20, v28
	v_mul_f32_e32 v21, v21, v29
	v_mul_f32_e32 v22, v22, v30
	v_mul_f32_e32 v23, v23, v31
	v_mul_f32_e32 v16, v16, v24
	v_mul_f32_e32 v17, v17, v25
	v_mul_f32_e32 v18, v18, v26
	v_mul_f32_e32 v19, v19, v27
	v_med3_f32 v20, v20, s52, v145
	v_med3_f32 v21, v21, s52, v145
	v_med3_f32 v22, v22, s52, v145
	v_med3_f32 v23, v23, s52, v145
	v_med3_f32 v16, v16, s52, v145
	v_med3_f32 v17, v17, s52, v145
	v_med3_f32 v18, v18, s52, v145
	v_med3_f32 v19, v19, s52, v145
	v_cvt_pk_fp8_f32 v132, v20, v21
	v_cvt_pk_fp8_f32 v132, v22, v23 op_sel:[0,0,1]
	v_cvt_pk_fp8_f32 v133, v16, v17
	v_cvt_pk_fp8_f32 v133, v18, v19 op_sel:[0,0,1]
	v_add_u32_e32 v28, 0xa0, v146
	v_mad_i64_i32 v[30:31], s[24:25], v28, s51, v[138:139]
	v_lshl_add_u64 v[30:31], v[30:31], 0, v[136:137]
	global_store_dwordx2 v[30:31], v[132:133], off
	v_mul_f32_e32 v4, v12, v4
	v_mul_f32_e32 v5, v13, v5
	v_mul_f32_e32 v6, v14, v6
	v_mul_f32_e32 v7, v15, v7
	v_mul_f32_e32 v0, v8, v0
	v_mul_f32_e32 v1, v9, v1
	v_mul_f32_e32 v2, v10, v2
	v_mul_f32_e32 v3, v11, v3
	v_mul_f32_e32 v12, s28, v12
	v_mul_f32_e32 v13, s28, v13
	v_mul_f32_e32 v14, s28, v14
	v_mul_f32_e32 v15, s28, v15
	v_mul_f32_e32 v8, s28, v8
	v_mul_f32_e32 v9, s28, v9
	v_mul_f32_e32 v10, s28, v10
	v_mul_f32_e32 v11, s28, v11
	v_exp_f32_e32 v12, v12
	v_exp_f32_e32 v13, v13
	v_exp_f32_e32 v14, v14
	v_exp_f32_e32 v15, v15
	v_exp_f32_e32 v8, v8
	v_exp_f32_e32 v9, v9
	v_exp_f32_e32 v10, v10
	v_exp_f32_e32 v11, v11
	v_fma_f32 v12, v12, s29, s29
	v_fma_f32 v13, v13, s29, s29
	v_fma_f32 v14, v14, s29, s29
	v_fma_f32 v15, v15, s29, s29
	v_fma_f32 v8, v8, s29, s29
	v_fma_f32 v9, v9, s29, s29
	v_fma_f32 v10, v10, s29, s29
	v_fma_f32 v11, v11, s29, s29
	v_rcp_f32_e32 v12, v12
	v_rcp_f32_e32 v13, v13
	v_rcp_f32_e32 v14, v14
	v_rcp_f32_e32 v15, v15
	v_rcp_f32_e32 v8, v8
	v_rcp_f32_e32 v9, v9
	v_rcp_f32_e32 v10, v10
	v_rcp_f32_e32 v11, v11
	v_mul_f32_e32 v4, v4, v12
	v_mul_f32_e32 v5, v5, v13
	v_mul_f32_e32 v6, v6, v14
	v_mul_f32_e32 v7, v7, v15
	v_mul_f32_e32 v0, v0, v8
	v_mul_f32_e32 v1, v1, v9
	v_mul_f32_e32 v2, v2, v10
	v_mul_f32_e32 v3, v3, v11
	v_med3_f32 v4, v4, s52, v145
	v_med3_f32 v5, v5, s52, v145
	v_med3_f32 v6, v6, s52, v145
	v_med3_f32 v7, v7, s52, v145
	v_med3_f32 v0, v0, s52, v145
	v_med3_f32 v1, v1, s52, v145
	v_med3_f32 v2, v2, s52, v145
	v_med3_f32 v3, v3, s52, v145
	v_cvt_pk_fp8_f32 v134, v4, v5
	v_cvt_pk_fp8_f32 v134, v6, v7 op_sel:[0,0,1]
	v_cvt_pk_fp8_f32 v135, v0, v1
	v_cvt_pk_fp8_f32 v135, v2, v3 op_sel:[0,0,1]
	v_add_u32_e32 v12, 0xb0, v146
	v_mad_i64_i32 v[14:15], s[24:25], v12, s51, v[138:139]
	v_lshl_add_u64 v[14:15], v[14:15], 0, v[136:137]
	v_readlane_b32 s58, v254, 11
	s_andn2_b64 vcc, exec, s[0:1]
	s_mov_b64 s[0:1], -1
	v_readlane_b32 s59, v254, 12
	global_store_dwordx2 v[14:15], v[134:135], off
	s_cbranch_vccnz .LBB0_186
	s_andn2_b64 vcc, exec, s[4:5]
	s_cbranch_vccnz .LBB0_185
	s_barrier
	s_branch .LBB0_185

; __device__ __forceinline__ float silu_f(float x) { return x * __builtin_amdgcn_rcpf(1.0f + __builtin_amdgcn_exp2f(-1.4426950408889634f * x)); }
; __device__ __forceinline__ float silu_f(float x) { return x * __builtin_amdgcn_rcpf(1.0f + __builtin_amdgcn_exp2f(-1.4426950408889634f * x)); }
; __device__ __forceinline__ float clamp8(float x) { return __builtin_amdgcn_fmed3f(x, -448.0f, 448.0f); }
; __device__ __forceinline__ unsigned pk4_fp8(float a, float b, float c, float d) {
;     int w = __builtin_amdgcn_cvt_pk_fp8_f32(clamp8(a), clamp8(b), 0, false); w = __builtin_amdgcn_cvt_pk_fp8_f32(clamp8(c), clamp8(d), w, true); return (unsigned)w; }
;     __device__ __forceinline__ void operator()(const f32x4 (&acc)[2][2][4][2], const Unit& u, int wr, int wc, int fr, int fq) const {
;         const int row0 = u.pm * BM + wr * 64 + fr, col0 = u.pn * HALF + wc * 32 + 8 * fq;
; #pragma unroll
;         for (int ai = 0; ai < 2; ++ai)
; #pragma unroll
;             for (int m = 0; m < 4; ++m) { unsigned char* rowp = O + (size_t)(row0 + ai * HALF + m * 16) * ldc + col0;
;                 const f32x4 g0 = acc[ai][0][m][0] * inv, g1 = acc[ai][0][m][1] * inv, u0 = acc[ai][1][m][0] * (inv * oscale), u1 = acc[ai][1][m][1] * (inv * oscale);
;                 unsigned w0 = pk4_fp8(silu_f(g0[0]) * u0[0], silu_f(g0[1]) * u0[1], silu_f(g0[2]) * u0[2], silu_f(g0[3]) * u0[3]);
;                 unsigned w1 = pk4_fp8(silu_f(g1[0]) * u1[0], silu_f(g1[1]) * u1[1], silu_f(g1[2]) * u1[2], silu_f(g1[3]) * u1[3]);
;                 typedef unsigned u32x2_t __attribute__((ext_vector_type(2))); *(u32x2_t*)rowp = (u32x2_t){w0, w1}; }
.LBB0_1400:
	v_mov_b32_e32 v132, v252
	s_lshl_b32 s15, s22, 8
	s_add_i32 s15, s15, s44
	v_and_or_b32 v146, v132, 15, s15
	s_lshl_b32 s15, s53, 7
	v_lshrrev_b32_e32 v132, 1, v132
	v_and_or_b32 v132, v132, 24, s15
	v_or_b32_e32 v136, s45, v132
	v_ashrrev_i32_e32 v137, 31, v136
	v_mov_b64_e32 v[138:139], s[6:7]
	v_mov_b32_e32 v133, s12
	v_mov_b32_e32 v135, s10
	v_mul_f32_e32 v133, s10, v133
	v_mul_f32_e32 v134, 0xbfb8aa3b, v135
	v_rcp_f32_e32 v133, v133
	s_nop 1
	v_readfirstlane_b32 s28, v134
	v_readfirstlane_b32 s29, v133
	s_nop 1
	v_mul_f32_e32 v116, v124, v116
	v_mul_f32_e32 v117, v125, v117
	v_mul_f32_e32 v118, v126, v118
	v_mul_f32_e32 v119, v127, v119
	v_mul_f32_e32 v112, v120, v112
	v_mul_f32_e32 v113, v121, v113
	v_mul_f32_e32 v114, v122, v114
	v_mul_f32_e32 v115, v123, v115
	v_mul_f32_e32 v124, s28, v124
	v_mul_f32_e32 v125, s28, v125
	v_mul_f32_e32 v126, s28, v126
	v_mul_f32_e32 v127, s28, v127
	v_mul_f32_e32 v120, s28, v120
	v_mul_f32_e32 v121, s28, v121
	v_mul_f32_e32 v122, s28, v122
	v_mul_f32_e32 v123, s28, v123
	v_exp_f32_e32 v124, v124
	v_exp_f32_e32 v125, v125
	v_exp_f32_e32 v126, v126
	v_exp_f32_e32 v127, v127
	v_exp_f32_e32 v120, v120
	v_exp_f32_e32 v121, v121
	v_exp_f32_e32 v122, v122
	v_exp_f32_e32 v123, v123
	v_fma_f32 v124, v124, s29, s29
	v_fma_f32 v125, v125, s29, s29
	v_fma_f32 v126, v126, s29, s29
	v_fma_f32 v127, v127, s29, s29
	v_fma_f32 v120, v120, s29, s29
	v_fma_f32 v121, v121, s29, s29
	v_fma_f32 v122, v122, s29, s29
	v_fma_f32 v123, v123, s29, s29
	v_rcp_f32_e32 v124, v124
	v_rcp_f32_e32 v125, v125
	v_rcp_f32_e32 v126, v126
	v_rcp_f32_e32 v127, v127
	v_rcp_f32_e32 v120, v120
	v_rcp_f32_e32 v121, v121
	v_rcp_f32_e32 v122, v122
	v_rcp_f32_e32 v123, v123
	v_mul_f32_e32 v116, v116, v124
	v_mul_f32_e32 v117, v117, v125
	v_mul_f32_e32 v118, v118, v126
	v_mul_f32_e32 v119, v119, v127
	v_mul_f32_e32 v112, v112, v120
	v_mul_f32_e32 v113, v113, v121
	v_mul_f32_e32 v114, v114, v122
	v_mul_f32_e32 v115, v115, v123
	v_med3_f32 v116, v116, s52, v145
	v_med3_f32 v117, v117, s52, v145
	v_med3_f32 v118, v118, s52, v145
	v_med3_f32 v119, v119, s52, v145
	v_med3_f32 v112, v112, s52, v145
	v_med3_f32 v113, v113, s52, v145
	v_med3_f32 v114, v114, s52, v145
	v_med3_f32 v115, v115, s52, v145
	v_cvt_pk_fp8_f32 v132, v116, v117
	v_cvt_pk_fp8_f32 v132, v118, v119 op_sel:[0,0,1]
	v_cvt_pk_fp8_f32 v133, v112, v113
	v_cvt_pk_fp8_f32 v133, v114, v115 op_sel:[0,0,1]
	v_mad_i64_i32 v[126:127], s[24:25], v146, s51, v[138:139]
	v_lshl_add_u64 v[126:127], v[126:127], 0, v[136:137]
	global_store_dwordx2 v[126:127], v[132:133], off
	v_mul_f32_e32 v100, v108, v100
	v_mul_f32_e32 v101, v109, v101
	v_mul_f32_e32 v102, v110, v102
	v_mul_f32_e32 v103, v111, v103
	v_mul_f32_e32 v96, v104, v96
	v_mul_f32_e32 v97, v105, v97
	v_mul_f32_e32 v98, v106, v98
	v_mul_f32_e32 v99, v107, v99
	v_mul_f32_e32 v108, s28, v108
	v_mul_f32_e32 v109, s28, v109
	v_mul_f32_e32 v110, s28, v110
	v_mul_f32_e32 v111, s28, v111
	v_mul_f32_e32 v104, s28, v104
	v_mul_f32_e32 v105, s28, v105
	v_mul_f32_e32 v106, s28, v106
	v_mul_f32_e32 v107, s28, v107
	v_exp_f32_e32 v108, v108
	v_exp_f32_e32 v109, v109
	v_exp_f32_e32 v110, v110
	v_exp_f32_e32 v111, v111
	v_exp_f32_e32 v104, v104
	v_exp_f32_e32 v105, v105
	v_exp_f32_e32 v106, v106
	v_exp_f32_e32 v107, v107
	v_fma_f32 v108, v108, s29, s29
	v_fma_f32 v109, v109, s29, s29
	v_fma_f32 v110, v110, s29, s29
	v_fma_f32 v111, v111, s29, s29
	v_fma_f32 v104, v104, s29, s29
	v_fma_f32 v105, v105, s29, s29
	v_fma_f32 v106, v106, s29, s29
	v_fma_f32 v107, v107, s29, s29
	v_rcp_f32_e32 v108, v108
	v_rcp_f32_e32 v109, v109
	v_rcp_f32_e32 v110, v110
	v_rcp_f32_e32 v111, v111
	v_rcp_f32_e32 v104, v104
	v_rcp_f32_e32 v105, v105
	v_rcp_f32_e32 v106, v106
	v_rcp_f32_e32 v107, v107
	v_mul_f32_e32 v100, v100, v108
	v_mul_f32_e32 v101, v101, v109
	v_mul_f32_e32 v102, v102, v110
	v_mul_f32_e32 v103, v103, v111
	v_mul_f32_e32 v96, v96, v104
	v_mul_f32_e32 v97, v97, v105
	v_mul_f32_e32 v98, v98, v106
	v_mul_f32_e32 v99, v99, v107
	v_med3_f32 v100, v100, s52, v145
	v_med3_f32 v101, v101, s52, v145
	v_med3_f32 v102, v102, s52, v145
	v_med3_f32 v103, v103, s52, v145
	v_med3_f32 v96, v96, s52, v145
	v_med3_f32 v97, v97, s52, v145
	v_med3_f32 v98, v98, s52, v145
	v_med3_f32 v99, v99, s52, v145
	v_cvt_pk_fp8_f32 v134, v100, v101
	v_cvt_pk_fp8_f32 v134, v102, v103 op_sel:[0,0,1]
	v_cvt_pk_fp8_f32 v135, v96, v97
	v_cvt_pk_fp8_f32 v135, v98, v99 op_sel:[0,0,1]
	v_add_u32_e32 v108, 0x10, v146
	v_mad_i64_i32 v[110:111], s[24:25], v108, s51, v[138:139]
	v_lshl_add_u64 v[110:111], v[110:111], 0, v[136:137]
	global_store_dwordx2 v[110:111], v[134:135], off
	v_mul_f32_e32 v84, v92, v84
	v_mul_f32_e32 v85, v93, v85
	v_mul_f32_e32 v86, v94, v86
	v_mul_f32_e32 v87, v95, v87
	v_mul_f32_e32 v80, v88, v80
	v_mul_f32_e32 v81, v89, v81
	v_mul_f32_e32 v82, v90, v82
	v_mul_f32_e32 v83, v91, v83
	v_mul_f32_e32 v92, s28, v92
	v_mul_f32_e32 v93, s28, v93
	v_mul_f32_e32 v94, s28, v94
	v_mul_f32_e32 v95, s28, v95
	v_mul_f32_e32 v88, s28, v88
	v_mul_f32_e32 v89, s28, v89
	v_mul_f32_e32 v90, s28, v90
	v_mul_f32_e32 v91, s28, v91
	v_exp_f32_e32 v92, v92
	v_exp_f32_e32 v93, v93
	v_exp_f32_e32 v94, v94
	v_exp_f32_e32 v95, v95
	v_exp_f32_e32 v88, v88
	v_exp_f32_e32 v89, v89
	v_exp_f32_e32 v90, v90
	v_exp_f32_e32 v91, v91
	v_fma_f32 v92, v92, s29, s29
	v_fma_f32 v93, v93, s29, s29
	v_fma_f32 v94, v94, s29, s29
	v_fma_f32 v95, v95, s29, s29
	v_fma_f32 v88, v88, s29, s29
	v_fma_f32 v89, v89, s29, s29
	v_fma_f32 v90, v90, s29, s29
	v_fma_f32 v91, v91, s29, s29
	v_rcp_f32_e32 v92, v92
	v_rcp_f32_e32 v93, v93
	v_rcp_f32_e32 v94, v94
	v_rcp_f32_e32 v95, v95
	v_rcp_f32_e32 v88, v88
; __device__ __forceinline__ float silu_f(float x) { return x * __builtin_amdgcn_rcpf(1.0f + __builtin_amdgcn_exp2f(-1.4426950408889634f * x)); }
; __device__ __forceinline__ float silu_f(float x) { return x * __builtin_amdgcn_rcpf(1.0f + __builtin_amdgcn_exp2f(-1.4426950408889634f * x)); }
; __device__ __forceinline__ float clamp8(float x) { return __builtin_amdgcn_fmed3f(x, -448.0f, 448.0f); }
; __device__ __forceinline__ unsigned pk4_fp8(float a, float b, float c, float d) {
;     int w = __builtin_amdgcn_cvt_pk_fp8_f32(clamp8(a), clamp8(b), 0, false); w = __builtin_amdgcn_cvt_pk_fp8_f32(clamp8(c), clamp8(d), w, true); return (unsigned)w; }
;     __device__ __forceinline__ void operator()(const f32x4 (&acc)[2][2][4][2], const Unit& u, int wr, int wc, int fr, int fq) const {
;         const int row0 = u.pm * BM + wr * 64 + fr, col0 = u.pn * HALF + wc * 32 + 8 * fq;
; #pragma unroll
;         for (int ai = 0; ai < 2; ++ai)
; #pragma unroll
;             for (int m = 0; m < 4; ++m) { unsigned char* rowp = O + (size_t)(row0 + ai * HALF + m * 16) * ldc + col0;
;                 const f32x4 g0 = acc[ai][0][m][0] * inv, g1 = acc[ai][0][m][1] * inv, u0 = acc[ai][1][m][0] * (inv * oscale), u1 = acc[ai][1][m][1] * (inv * oscale);
;                 unsigned w0 = pk4_fp8(silu_f(g0[0]) * u0[0], silu_f(g0[1]) * u0[1], silu_f(g0[2]) * u0[2], silu_f(g0[3]) * u0[3]);
;                 unsigned w1 = pk4_fp8(silu_f(g1[0]) * u1[0], silu_f(g1[1]) * u1[1], silu_f(g1[2]) * u1[2], silu_f(g1[3]) * u1[3]);
;                 typedef unsigned u32x2_t __attribute__((ext_vector_type(2))); *(u32x2_t*)rowp = (u32x2_t){w0, w1}; }
	v_rcp_f32_e32 v89, v89
	v_rcp_f32_e32 v90, v90
	v_rcp_f32_e32 v91, v91
	v_mul_f32_e32 v84, v84, v92
	v_mul_f32_e32 v85, v85, v93
	v_mul_f32_e32 v86, v86, v94
	v_mul_f32_e32 v87, v87, v95
	v_mul_f32_e32 v80, v80, v88
	v_mul_f32_e32 v81, v81, v89
	v_mul_f32_e32 v82, v82, v90
	v_mul_f32_e32 v83, v83, v91
	v_med3_f32 v84, v84, s52, v145
	v_med3_f32 v85, v85, s52, v145
	v_med3_f32 v86, v86, s52, v145
	v_med3_f32 v87, v87, s52, v145
	v_med3_f32 v80, v80, s52, v145
	v_med3_f32 v81, v81, s52, v145
	v_med3_f32 v82, v82, s52, v145
	v_med3_f32 v83, v83, s52, v145
	v_cvt_pk_fp8_f32 v132, v84, v85
	v_cvt_pk_fp8_f32 v132, v86, v87 op_sel:[0,0,1]
	v_cvt_pk_fp8_f32 v133, v80, v81
	v_cvt_pk_fp8_f32 v133, v82, v83 op_sel:[0,0,1]
	v_add_u32_e32 v92, 0x20, v146
	v_mad_i64_i32 v[94:95], s[24:25], v92, s51, v[138:139]
	v_lshl_add_u64 v[94:95], v[94:95], 0, v[136:137]
	global_store_dwordx2 v[94:95], v[132:133], off
	v_mul_f32_e32 v68, v76, v68
	v_mul_f32_e32 v69, v77, v69
	v_mul_f32_e32 v70, v78, v70
	v_mul_f32_e32 v71, v79, v71
	v_mul_f32_e32 v64, v72, v64
	v_mul_f32_e32 v65, v73, v65
	v_mul_f32_e32 v66, v74, v66
	v_mul_f32_e32 v67, v75, v67
	v_mul_f32_e32 v76, s28, v76
	v_mul_f32_e32 v77, s28, v77
	v_mul_f32_e32 v78, s28, v78
	v_mul_f32_e32 v79, s28, v79
	v_mul_f32_e32 v72, s28, v72
	v_mul_f32_e32 v73, s28, v73
	v_mul_f32_e32 v74, s28, v74
	v_mul_f32_e32 v75, s28, v75
	v_exp_f32_e32 v76, v76
	v_exp_f32_e32 v77, v77
	v_exp_f32_e32 v78, v78
	v_exp_f32_e32 v79, v79
	v_exp_f32_e32 v72, v72
	v_exp_f32_e32 v73, v73
	v_exp_f32_e32 v74, v74
	v_exp_f32_e32 v75, v75
	v_fma_f32 v76, v76, s29, s29
	v_fma_f32 v77, v77, s29, s29
	v_fma_f32 v78, v78, s29, s29
	v_fma_f32 v79, v79, s29, s29
	v_fma_f32 v72, v72, s29, s29
	v_fma_f32 v73, v73, s29, s29
	v_fma_f32 v74, v74, s29, s29
	v_fma_f32 v75, v75, s29, s29
	v_rcp_f32_e32 v76, v76
	v_rcp_f32_e32 v77, v77
	v_rcp_f32_e32 v78, v78
	v_rcp_f32_e32 v79, v79
	v_rcp_f32_e32 v72, v72
	v_rcp_f32_e32 v73, v73
	v_rcp_f32_e32 v74, v74
	v_rcp_f32_e32 v75, v75
	v_mul_f32_e32 v68, v68, v76
	v_mul_f32_e32 v69, v69, v77
	v_mul_f32_e32 v70, v70, v78
	v_mul_f32_e32 v71, v71, v79
	v_mul_f32_e32 v64, v64, v72
	v_mul_f32_e32 v65, v65, v73
	v_mul_f32_e32 v66, v66, v74
	v_mul_f32_e32 v67, v67, v75
	v_med3_f32 v68, v68, s52, v145
	v_med3_f32 v69, v69, s52, v145
	v_med3_f32 v70, v70, s52, v145
	v_med3_f32 v71, v71, s52, v145
	v_med3_f32 v64, v64, s52, v145
	v_med3_f32 v65, v65, s52, v145
	v_med3_f32 v66, v66, s52, v145
	v_med3_f32 v67, v67, s52, v145
	v_cvt_pk_fp8_f32 v134, v68, v69
	v_cvt_pk_fp8_f32 v134, v70, v71 op_sel:[0,0,1]
	v_cvt_pk_fp8_f32 v135, v64, v65
	v_cvt_pk_fp8_f32 v135, v66, v67 op_sel:[0,0,1]
	v_add_u32_e32 v76, 0x30, v146
	v_mad_i64_i32 v[78:79], s[24:25], v76, s51, v[138:139]
	v_lshl_add_u64 v[78:79], v[78:79], 0, v[136:137]
	global_store_dwordx2 v[78:79], v[134:135], off
	v_mul_f32_e32 v52, v60, v52
	v_mul_f32_e32 v53, v61, v53
	v_mul_f32_e32 v54, v62, v54
	v_mul_f32_e32 v55, v63, v55
	v_mul_f32_e32 v48, v56, v48
	v_mul_f32_e32 v49, v57, v49
	v_mul_f32_e32 v50, v58, v50
	v_mul_f32_e32 v51, v59, v51
	v_mul_f32_e32 v60, s28, v60
	v_mul_f32_e32 v61, s28, v61
	v_mul_f32_e32 v62, s28, v62
	v_mul_f32_e32 v63, s28, v63
	v_mul_f32_e32 v56, s28, v56
	v_mul_f32_e32 v57, s28, v57
	v_mul_f32_e32 v58, s28, v58
	v_mul_f32_e32 v59, s28, v59
	v_exp_f32_e32 v60, v60
	v_exp_f32_e32 v61, v61
	v_exp_f32_e32 v62, v62
	v_exp_f32_e32 v63, v63
	v_exp_f32_e32 v56, v56
	v_exp_f32_e32 v57, v57
	v_exp_f32_e32 v58, v58
	v_exp_f32_e32 v59, v59
	v_fma_f32 v60, v60, s29, s29
	v_fma_f32 v61, v61, s29, s29
	v_fma_f32 v62, v62, s29, s29
	v_fma_f32 v63, v63, s29, s29
	v_fma_f32 v56, v56, s29, s29
	v_fma_f32 v57, v57, s29, s29
	v_fma_f32 v58, v58, s29, s29
	v_fma_f32 v59, v59, s29, s29
	v_rcp_f32_e32 v60, v60
	v_rcp_f32_e32 v61, v61
	v_rcp_f32_e32 v62, v62
	v_rcp_f32_e32 v63, v63
	v_rcp_f32_e32 v56, v56
	v_rcp_f32_e32 v57, v57
	v_rcp_f32_e32 v58, v58
	v_rcp_f32_e32 v59, v59
	v_mul_f32_e32 v52, v52, v60
	v_mul_f32_e32 v53, v53, v61
	v_mul_f32_e32 v54, v54, v62
	v_mul_f32_e32 v55, v55, v63
	v_mul_f32_e32 v48, v48, v56
	v_mul_f32_e32 v49, v49, v57
	v_mul_f32_e32 v50, v50, v58
	v_mul_f32_e32 v51, v51, v59
	v_med3_f32 v52, v52, s52, v145
	v_med3_f32 v53, v53, s52, v145
	v_med3_f32 v54, v54, s52, v145
	v_med3_f32 v55, v55, s52, v145
	v_med3_f32 v48, v48, s52, v145
	v_med3_f32 v49, v49, s52, v145
	v_med3_f32 v50, v50, s52, v145
	v_med3_f32 v51, v51, s52, v145
	v_cvt_pk_fp8_f32 v132, v52, v53
	v_cvt_pk_fp8_f32 v132, v54, v55 op_sel:[0,0,1]
	v_cvt_pk_fp8_f32 v133, v48, v49
	v_cvt_pk_fp8_f32 v133, v50, v51 op_sel:[0,0,1]
	v_add_u32_e32 v60, 0x80, v146
	v_mad_i64_i32 v[62:63], s[24:25], v60, s51, v[138:139]
	v_lshl_add_u64 v[62:63], v[62:63], 0, v[136:137]
	global_store_dwordx2 v[62:63], v[132:133], off
	v_mul_f32_e32 v36, v44, v36
	v_mul_f32_e32 v37, v45, v37
	v_mul_f32_e32 v38, v46, v38
	v_mul_f32_e32 v39, v47, v39
	v_mul_f32_e32 v32, v40, v32
	v_mul_f32_e32 v33, v41, v33
	v_mul_f32_e32 v34, v42, v34
	v_mul_f32_e32 v35, v43, v35
	v_mul_f32_e32 v44, s28, v44
	v_mul_f32_e32 v45, s28, v45
	v_mul_f32_e32 v46, s28, v46
	v_mul_f32_e32 v47, s28, v47
	v_mul_f32_e32 v40, s28, v40
	v_mul_f32_e32 v41, s28, v41
	v_mul_f32_e32 v42, s28, v42
	v_mul_f32_e32 v43, s28, v43
	v_exp_f32_e32 v44, v44
	v_exp_f32_e32 v45, v45
	v_exp_f32_e32 v46, v46
	v_exp_f32_e32 v47, v47
	v_exp_f32_e32 v40, v40
; __device__ __forceinline__ float silu_f(float x) { return x * __builtin_amdgcn_rcpf(1.0f + __builtin_amdgcn_exp2f(-1.4426950408889634f * x)); }
; __device__ __forceinline__ float silu_f(float x) { return x * __builtin_amdgcn_rcpf(1.0f + __builtin_amdgcn_exp2f(-1.4426950408889634f * x)); }
; __device__ __forceinline__ float clamp8(float x) { return __builtin_amdgcn_fmed3f(x, -448.0f, 448.0f); }
; __device__ __forceinline__ unsigned pk4_fp8(float a, float b, float c, float d) {
;     int w = __builtin_amdgcn_cvt_pk_fp8_f32(clamp8(a), clamp8(b), 0, false); w = __builtin_amdgcn_cvt_pk_fp8_f32(clamp8(c), clamp8(d), w, true); return (unsigned)w; }
;     __device__ __forceinline__ void operator()(const f32x4 (&acc)[2][2][4][2], const Unit& u, int wr, int wc, int fr, int fq) const {
;         const int row0 = u.pm * BM + wr * 64 + fr, col0 = u.pn * HALF + wc * 32 + 8 * fq;
; #pragma unroll
;         for (int ai = 0; ai < 2; ++ai)
; #pragma unroll
;             for (int m = 0; m < 4; ++m) { unsigned char* rowp = O + (size_t)(row0 + ai * HALF + m * 16) * ldc + col0;
;                 const f32x4 g0 = acc[ai][0][m][0] * inv, g1 = acc[ai][0][m][1] * inv, u0 = acc[ai][1][m][0] * (inv * oscale), u1 = acc[ai][1][m][1] * (inv * oscale);
;                 unsigned w0 = pk4_fp8(silu_f(g0[0]) * u0[0], silu_f(g0[1]) * u0[1], silu_f(g0[2]) * u0[2], silu_f(g0[3]) * u0[3]);
;                 unsigned w1 = pk4_fp8(silu_f(g1[0]) * u1[0], silu_f(g1[1]) * u1[1], silu_f(g1[2]) * u1[2], silu_f(g1[3]) * u1[3]);
;                 typedef unsigned u32x2_t __attribute__((ext_vector_type(2))); *(u32x2_t*)rowp = (u32x2_t){w0, w1}; }
	v_exp_f32_e32 v41, v41
	v_exp_f32_e32 v42, v42
	v_exp_f32_e32 v43, v43
	v_fma_f32 v44, v44, s29, s29
	v_fma_f32 v45, v45, s29, s29
	v_fma_f32 v46, v46, s29, s29
	v_fma_f32 v47, v47, s29, s29
	v_fma_f32 v40, v40, s29, s29
	v_fma_f32 v41, v41, s29, s29
	v_fma_f32 v42, v42, s29, s29
	v_fma_f32 v43, v43, s29, s29
	v_rcp_f32_e32 v44, v44
	v_rcp_f32_e32 v45, v45
	v_rcp_f32_e32 v46, v46
	v_rcp_f32_e32 v47, v47
	v_rcp_f32_e32 v40, v40
	v_rcp_f32_e32 v41, v41
	v_rcp_f32_e32 v42, v42
	v_rcp_f32_e32 v43, v43
	v_mul_f32_e32 v36, v36, v44
	v_mul_f32_e32 v37, v37, v45
	v_mul_f32_e32 v38, v38, v46
	v_mul_f32_e32 v39, v39, v47
	v_mul_f32_e32 v32, v32, v40
	v_mul_f32_e32 v33, v33, v41
	v_mul_f32_e32 v34, v34, v42
	v_mul_f32_e32 v35, v35, v43
	v_med3_f32 v36, v36, s52, v145
	v_med3_f32 v37, v37, s52, v145
	v_med3_f32 v38, v38, s52, v145
	v_med3_f32 v39, v39, s52, v145
	v_med3_f32 v32, v32, s52, v145
	v_med3_f32 v33, v33, s52, v145
	v_med3_f32 v34, v34, s52, v145
	v_med3_f32 v35, v35, s52, v145
	v_cvt_pk_fp8_f32 v134, v36, v37
	v_cvt_pk_fp8_f32 v134, v38, v39 op_sel:[0,0,1]
	v_cvt_pk_fp8_f32 v135, v32, v33
	v_cvt_pk_fp8_f32 v135, v34, v35 op_sel:[0,0,1]
	v_add_u32_e32 v44, 0x90, v146
	v_mad_i64_i32 v[46:47], s[24:25], v44, s51, v[138:139]
	v_lshl_add_u64 v[46:47], v[46:47], 0, v[136:137]
	global_store_dwordx2 v[46:47], v[134:135], off
	v_mul_f32_e32 v20, v28, v20
	v_mul_f32_e32 v21, v29, v21
	v_mul_f32_e32 v22, v30, v22
	v_mul_f32_e32 v23, v31, v23
	v_mul_f32_e32 v16, v24, v16
	v_mul_f32_e32 v17, v25, v17
	v_mul_f32_e32 v18, v26, v18
	v_mul_f32_e32 v19, v27, v19
	v_mul_f32_e32 v28, s28, v28
	v_mul_f32_e32 v29, s28, v29
	v_mul_f32_e32 v30, s28, v30
	v_mul_f32_e32 v31, s28, v31
	v_mul_f32_e32 v24, s28, v24
	v_mul_f32_e32 v25, s28, v25
	v_mul_f32_e32 v26, s28, v26
	v_mul_f32_e32 v27, s28, v27
	v_exp_f32_e32 v28, v28
	v_exp_f32_e32 v29, v29
	v_exp_f32_e32 v30, v30
	v_exp_f32_e32 v31, v31
	v_exp_f32_e32 v24, v24
	v_exp_f32_e32 v25, v25
	v_exp_f32_e32 v26, v26
	v_exp_f32_e32 v27, v27
	v_fma_f32 v28, v28, s29, s29
	v_fma_f32 v29, v29, s29, s29
	v_fma_f32 v30, v30, s29, s29
	v_fma_f32 v31, v31, s29, s29
	v_fma_f32 v24, v24, s29, s29
	v_fma_f32 v25, v25, s29, s29
	v_fma_f32 v26, v26, s29, s29
	v_fma_f32 v27, v27, s29, s29
	v_rcp_f32_e32 v28, v28
	v_rcp_f32_e32 v29, v29
	v_rcp_f32_e32 v30, v30
	v_rcp_f32_e32 v31, v31
	v_rcp_f32_e32 v24, v24
	v_rcp_f32_e32 v25, v25
	v_rcp_f32_e32 v26, v26
	v_rcp_f32_e32 v27, v27
	v_mul_f32_e32 v20, v20, v28
	v_mul_f32_e32 v21, v21, v29
	v_mul_f32_e32 v22, v22, v30
	v_mul_f32_e32 v23, v23, v31
	v_mul_f32_e32 v16, v16, v24
	v_mul_f32_e32 v17, v17, v25
	v_mul_f32_e32 v18, v18, v26
	v_mul_f32_e32 v19, v19, v27
	v_med3_f32 v20, v20, s52, v145
	v_med3_f32 v21, v21, s52, v145
	v_med3_f32 v22, v22, s52, v145
	v_med3_f32 v23, v23, s52, v145
	v_med3_f32 v16, v16, s52, v145
	v_med3_f32 v17, v17, s52, v145
	v_med3_f32 v18, v18, s52, v145
	v_med3_f32 v19, v19, s52, v145
	v_cvt_pk_fp8_f32 v132, v20, v21
	v_cvt_pk_fp8_f32 v132, v22, v23 op_sel:[0,0,1]
	v_cvt_pk_fp8_f32 v133, v16, v17
	v_cvt_pk_fp8_f32 v133, v18, v19 op_sel:[0,0,1]
	v_add_u32_e32 v28, 0xa0, v146
	v_mad_i64_i32 v[30:31], s[24:25], v28, s51, v[138:139]
	v_lshl_add_u64 v[30:31], v[30:31], 0, v[136:137]
	global_store_dwordx2 v[30:31], v[132:133], off
	v_mul_f32_e32 v4, v12, v4
	v_mul_f32_e32 v5, v13, v5
	v_mul_f32_e32 v6, v14, v6
	v_mul_f32_e32 v7, v15, v7
	v_mul_f32_e32 v0, v8, v0
	v_mul_f32_e32 v1, v9, v1
	v_mul_f32_e32 v2, v10, v2
	v_mul_f32_e32 v3, v11, v3
	v_mul_f32_e32 v12, s28, v12
	v_mul_f32_e32 v13, s28, v13
	v_mul_f32_e32 v14, s28, v14
	v_mul_f32_e32 v15, s28, v15
	v_mul_f32_e32 v8, s28, v8
	v_mul_f32_e32 v9, s28, v9
	v_mul_f32_e32 v10, s28, v10
	v_mul_f32_e32 v11, s28, v11
	v_exp_f32_e32 v12, v12
	v_exp_f32_e32 v13, v13
	v_exp_f32_e32 v14, v14
	v_exp_f32_e32 v15, v15
	v_exp_f32_e32 v8, v8
	v_exp_f32_e32 v9, v9
	v_exp_f32_e32 v10, v10
	v_exp_f32_e32 v11, v11
	v_fma_f32 v12, v12, s29, s29
	v_fma_f32 v13, v13, s29, s29
	v_fma_f32 v14, v14, s29, s29
	v_fma_f32 v15, v15, s29, s29
	v_fma_f32 v8, v8, s29, s29
	v_fma_f32 v9, v9, s29, s29
	v_fma_f32 v10, v10, s29, s29
	v_fma_f32 v11, v11, s29, s29
	v_rcp_f32_e32 v12, v12
	v_rcp_f32_e32 v13, v13
	v_rcp_f32_e32 v14, v14
	v_rcp_f32_e32 v15, v15
	v_rcp_f32_e32 v8, v8
	v_rcp_f32_e32 v9, v9
	v_rcp_f32_e32 v10, v10
	v_rcp_f32_e32 v11, v11
	v_mul_f32_e32 v4, v4, v12
	v_mul_f32_e32 v5, v5, v13
	v_mul_f32_e32 v6, v6, v14
	v_mul_f32_e32 v7, v7, v15
	v_mul_f32_e32 v0, v0, v8
	v_mul_f32_e32 v1, v1, v9
	v_mul_f32_e32 v2, v2, v10
	v_mul_f32_e32 v3, v3, v11
	v_med3_f32 v4, v4, s52, v145
	v_med3_f32 v5, v5, s52, v145
	v_med3_f32 v6, v6, s52, v145
	v_med3_f32 v7, v7, s52, v145
	v_med3_f32 v0, v0, s52, v145
	v_med3_f32 v1, v1, s52, v145
	v_med3_f32 v2, v2, s52, v145
	v_med3_f32 v3, v3, s52, v145
	v_cvt_pk_fp8_f32 v134, v4, v5
	v_cvt_pk_fp8_f32 v134, v6, v7 op_sel:[0,0,1]
	v_cvt_pk_fp8_f32 v135, v0, v1
	v_cvt_pk_fp8_f32 v135, v2, v3 op_sel:[0,0,1]
	v_add_u32_e32 v12, 0xb0, v146
	v_mad_i64_i32 v[14:15], s[24:25], v12, s51, v[138:139]
	v_lshl_add_u64 v[14:15], v[14:15], 0, v[136:137]
	v_readlane_b32 s58, v254, 11
	s_andn2_b64 vcc, exec, s[0:1]
	s_mov_b64 s[0:1], -1
	v_readlane_b32 s59, v254, 12
	global_store_dwordx2 v[14:15], v[134:135], off
	s_cbranch_vccnz .LBB0_1393
	s_andn2_b64 vcc, exec, s[4:5]
	s_cbranch_vccnz .LBB0_1392
	s_barrier
	s_branch .LBB0_1392
